# scan-after-attention split plus write-through (sc0 sc1) on the scan state stores so the late scan leaves nothing dirty for the P5 seam flush
# baseline (speedup 1.0000x reference)
.LBB0_1109:
	s_or_b64 exec, exec, s[14:15]
	s_and_saveexec_b64 s[12:13], s[6:7]
	ds_write_b128 v1, v[2:5] offset:32768
	s_or_b64 exec, exec, s[12:13]
	s_waitcnt lgkmcnt(0)
	s_barrier
	s_and_saveexec_b64 s[12:13], s[30:31]
	s_cbranch_execz .LBB0_1114
	s_and_b32 s14, s22, 0x78
	v_or_b32_e32 v2, s14, v150
	s_and_b64 s[14:15], s[16:17], exec
	v_or_b32_e32 v4, s18, v151
	s_cselect_b32 s20, 0x7f, 1
	s_cselect_b32 s14, -1, 1
	s_cselect_b32 s15, -1, 0
	s_and_b32 s18, s22, 0xfffffe00
	s_or_b32 s18, s18, s0
	s_ashr_i32 s19, s18, 31
	s_lshl_b64 s[18:19], s[18:19], 15
	s_add_u32 s18, s84, s18
	s_addc_u32 s19, s85, s19
	v_lshlrev_b32_e32 v6, 8, v2
	v_lshl_add_u64 v[2:3], s[18:19], 0, v[6:7]
	v_lshlrev_b32_e32 v6, 1, v4
	v_lshl_add_u64 v[2:3], v[2:3], 0, v[6:7]
	s_lshl_b32 s0, s20, 17
	v_lshl_add_u64 v[2:3], v[2:3], 0, s[0:1]
	v_add_co_u32_e32 v4, vcc, s27, v2
	v_lshl_add_u32 v6, s20, 8, v152
	s_nop 0
	v_addc_co_u32_e32 v5, vcc, -1, v3, vcc
	s_lshl_b64 s[20:21], s[14:15], 17
	v_lshl_add_u64 v[2:3], v[2:3], 0, s[8:9]
	global_load_dword v4, v[4:5], off
	v_lshl_add_u64 v[118:119], v[2:3], 0, s[20:21]
	v_lshl_add_u64 v[122:123], v[118:119], 0, s[20:21]
	v_lshl_add_u64 v[126:127], v[122:123], 0, s[20:21]
	v_lshl_add_u64 v[130:131], v[126:127], 0, s[20:21]
	global_load_dword v162, v[118:119], off
	global_load_dword v164, v[122:123], off
	global_load_dword v166, v[126:127], off
	global_load_dword v168, v[130:131], off
	v_lshl_add_u64 v[134:135], v[130:131], 0, s[20:21]
	global_load_dword v170, v[134:135], off
	v_lshl_add_u64 v[136:137], v[134:135], 0, s[20:21]
	global_load_dword v172, v[136:137], off
	v_lshl_add_u64 v[142:143], v[136:137], 0, s[20:21]
	v_lshl_add_u64 v[146:147], v[142:143], 0, s[20:21]
	v_lshl_add_u64 v[160:161], v[146:147], 0, s[20:21]
	global_load_dword v174, v[142:143], off
	v_lshl_add_u64 v[110:111], v[160:161], 0, s[20:21]
	v_lshl_add_u64 v[106:107], v[110:111], 0, s[20:21]
	v_lshl_add_u64 v[102:103], v[106:107], 0, s[20:21]
	global_load_dword v176, v[146:147], off
	v_lshl_add_u64 v[98:99], v[102:103], 0, s[20:21]
	v_lshl_add_u64 v[94:95], v[98:99], 0, s[20:21]
	v_lshl_add_u64 v[90:91], v[94:95], 0, s[20:21]
	global_load_dword v178, v[160:161], off
	v_lshl_add_u64 v[86:87], v[90:91], 0, s[20:21]
	v_lshl_add_u64 v[82:83], v[86:87], 0, s[20:21]
	v_lshl_add_u64 v[78:79], v[82:83], 0, s[20:21]
	v_lshl_add_u64 v[74:75], v[78:79], 0, s[20:21]
	v_lshl_add_u64 v[70:71], v[74:75], 0, s[20:21]
	v_lshl_add_u64 v[66:67], v[70:71], 0, s[20:21]
	v_lshl_add_u64 v[62:63], v[66:67], 0, s[20:21]
	v_lshl_add_u64 v[58:59], v[62:63], 0, s[20:21]
	global_load_dword v180, v[110:111], off
	v_lshl_add_u64 v[54:55], v[58:59], 0, s[20:21]
	v_lshl_add_u64 v[50:51], v[54:55], 0, s[20:21]
	v_lshl_add_u64 v[46:47], v[50:51], 0, s[20:21]
	global_load_dword v182, v[106:107], off
	v_lshl_add_u64 v[42:43], v[46:47], 0, s[20:21]
	v_lshl_add_u64 v[38:39], v[42:43], 0, s[20:21]
	v_lshl_add_u64 v[34:35], v[38:39], 0, s[20:21]
	global_load_dword v184, v[102:103], off
	v_lshl_add_u64 v[32:33], v[34:35], 0, s[20:21]
	v_lshl_add_u64 v[30:31], v[32:33], 0, s[20:21]
	v_lshl_add_u64 v[28:29], v[30:31], 0, s[20:21]
	global_load_dword v186, v[98:99], off
	v_lshl_add_u64 v[148:149], v[28:29], 0, s[20:21]
	v_lshl_add_u64 v[144:145], v[148:149], 0, s[20:21]
	v_lshl_add_u64 v[140:141], v[144:145], 0, s[20:21]
	v_lshl_add_u64 v[138:139], v[140:141], 0, s[20:21]
	v_lshl_add_u64 v[132:133], v[138:139], 0, s[20:21]
	v_lshl_add_u64 v[128:129], v[132:133], 0, s[20:21]
	v_lshl_add_u64 v[124:125], v[128:129], 0, s[20:21]
	v_lshl_add_u64 v[120:121], v[124:125], 0, s[20:21]
	global_load_dword v188, v[94:95], off
	v_lshl_add_u64 v[116:117], v[120:121], 0, s[20:21]
	v_lshl_add_u64 v[112:113], v[116:117], 0, s[20:21]
	v_lshl_add_u64 v[108:109], v[112:113], 0, s[20:21]
	global_load_dword v190, v[90:91], off
	v_lshl_add_u64 v[104:105], v[108:109], 0, s[20:21]
	v_lshl_add_u64 v[100:101], v[104:105], 0, s[20:21]
	v_lshl_add_u64 v[96:97], v[100:101], 0, s[20:21]
	global_load_dword v192, v[86:87], off
	v_lshl_add_u64 v[92:93], v[96:97], 0, s[20:21]
	v_lshl_add_u64 v[88:89], v[92:93], 0, s[20:21]
	v_lshl_add_u64 v[84:85], v[88:89], 0, s[20:21]
	global_load_dword v194, v[82:83], off
	v_lshl_add_u64 v[80:81], v[84:85], 0, s[20:21]
	v_lshl_add_u64 v[76:77], v[80:81], 0, s[20:21]
	v_lshl_add_u64 v[72:73], v[76:77], 0, s[20:21]
	v_lshl_add_u64 v[68:69], v[72:73], 0, s[20:21]
	v_lshl_add_u64 v[64:65], v[68:69], 0, s[20:21]
	v_lshl_add_u64 v[60:61], v[64:65], 0, s[20:21]
	v_lshl_add_u64 v[56:57], v[60:61], 0, s[20:21]
	v_lshl_add_u64 v[52:53], v[56:57], 0, s[20:21]
	global_load_dword v196, v[78:79], off
	v_lshl_add_u64 v[48:49], v[52:53], 0, s[20:21]
	ds_read_b64 v[224:225], v6
	v_lshl_add_u64 v[44:45], v[48:49], 0, s[20:21]
	v_lshl_add_u64 v[40:41], v[44:45], 0, s[20:21]
	global_load_dword v198, v[74:75], off
	v_lshl_add_u64 v[36:37], v[40:41], 0, s[20:21]
	v_lshl_add_u64 v[26:27], v[36:37], 0, s[20:21]
	s_waitcnt vmcnt(19)
	v_lshlrev_b32_e32 v222, 16, v4
	v_and_b32_e32 v223, 0xffff0000, v4
	s_waitcnt vmcnt(18)
	v_lshlrev_b32_e32 v226, 16, v162
	v_and_b32_e32 v227, 0xffff0000, v162
	v_lshl_add_u64 v[4:5], v[26:27], 0, s[20:21]
	s_waitcnt lgkmcnt(0)
	v_pk_fma_f32 v[222:223], v[224:225], v[222:223], v[226:227]
	global_load_dword v200, v[70:71], off
	v_lshl_add_u64 v[24:25], v[4:5], 0, s[20:21]
	v_cvt_pk_bf16_f32 v162, v222, v223
	global_load_dword v202, v[66:67], off
	global_load_dword v204, v[62:63], off
	global_load_dword v206, v[58:59], off
	global_load_dword v208, v[54:55], off
	global_load_dword v210, v[50:51], off
	global_load_dword v212, v[46:47], off
	global_load_dword v214, v[42:43], off
	global_load_dword v216, v[38:39], off
	global_load_dword v219, v[34:35], off
	global_load_dword v221, v[32:33], off
	global_load_dword v115, v[30:31], off
	global_load_dword v114, v[28:29], off
	global_load_dword v220, v[148:149], off
	global_load_dword v218, v[144:145], off
	global_load_dword v217, v[140:141], off
	global_load_dword v215, v[138:139], off
	global_load_dword v213, v[132:133], off
	global_load_dword v211, v[128:129], off
	global_load_dword v209, v[124:125], off
	global_load_dword v207, v[120:121], off
	global_load_dword v205, v[116:117], off
	global_load_dword v203, v[112:113], off
	global_load_dword v201, v[108:109], off
	global_load_dword v199, v[104:105], off
	global_load_dword v197, v[100:101], off
	global_load_dword v195, v[96:97], off
	global_load_dword v193, v[92:93], off
	global_load_dword v191, v[88:89], off
	global_load_dword v189, v[84:85], off
	global_load_dword v187, v[80:81], off
	global_load_dword v185, v[76:77], off
	global_load_dword v183, v[72:73], off
	global_load_dword v181, v[68:69], off
	global_load_dword v179, v[64:65], off
	global_load_dword v177, v[60:61], off
	global_load_dword v175, v[56:57], off
	global_load_dword v173, v[52:53], off
	global_load_dword v171, v[48:49], off
	global_load_dword v169, v[44:45], off
	global_load_dword v167, v[40:41], off
	global_load_dword v165, v[36:37], off
	global_load_dword v163, v[26:27], off
	global_load_dword v21, v[4:5], off
	global_load_dword v23, v[24:25], off
	s_waitcnt vmcnt(62)
	v_lshlrev_b32_e32 v224, 16, v164
	global_store_dword v[118:119], v162, off sc0 sc1
	v_lshl_add_u32 v118, s14, 8, v6
	ds_read_b64 v[118:119], v118
	v_and_b32_e32 v225, 0xffff0000, v164
	v_lshl_add_u32 v162, s14, 9, v6
	s_mul_i32 s0, s14, 0x300
	v_lshl_add_u32 v230, s14, 10, v6
	v_add_u32_e32 v164, s0, v6
	ds_read_b64 v[226:227], v162
	ds_read_b64 v[228:229], v164
	ds_read_b64 v[230:231], v230
	s_waitcnt lgkmcnt(3)
	v_pk_fma_f32 v[118:119], v[222:223], v[118:119], v[224:225]
	s_mul_i32 s0, s14, 0x500
	v_cvt_pk_bf16_f32 v162, v118, v119
	global_store_dword v[122:123], v162, off sc0 sc1
	s_waitcnt vmcnt(62)
	v_lshlrev_b32_e32 v122, 16, v166
	v_and_b32_e32 v123, 0xffff0000, v166
	s_waitcnt lgkmcnt(2)
	v_pk_fma_f32 v[118:119], v[118:119], v[226:227], v[122:123]
	v_and_b32_e32 v123, 0xffff0000, v168
	v_cvt_pk_bf16_f32 v122, v118, v119
	global_store_dword v[126:127], v122, off sc0 sc1
	v_lshlrev_b32_e32 v122, 16, v168
	s_waitcnt lgkmcnt(1)
	v_pk_fma_f32 v[118:119], v[118:119], v[228:229], v[122:123]
	s_waitcnt vmcnt(62)
	v_and_b32_e32 v123, 0xffff0000, v170
	v_cvt_pk_bf16_f32 v122, v118, v119
	global_store_dword v[130:131], v122, off sc0 sc1
	v_lshlrev_b32_e32 v122, 16, v170
	s_waitcnt lgkmcnt(0)
	v_pk_fma_f32 v[118:119], v[118:119], v[230:231], v[122:123]
	s_waitcnt vmcnt(62)
	v_lshlrev_b32_e32 v126, 16, v172
	v_cvt_pk_bf16_f32 v122, v118, v119
	global_store_dword v[134:135], v122, off sc0 sc1
	v_add_u32_e32 v122, s0, v6
	ds_read_b64 v[122:123], v122
	s_mul_i32 s0, s14, 0x600
	v_add_u32_e32 v130, s0, v6
	s_mul_i32 s0, s14, 0x700
	v_and_b32_e32 v127, 0xffff0000, v172
	v_add_u32_e32 v134, s0, v6
	v_lshl_add_u32 v162, s14, 11, v6
	ds_read_b64 v[130:131], v130
	ds_read_b64 v[134:135], v134
	ds_read_b64 v[222:223], v162
	s_waitcnt lgkmcnt(3)
	v_pk_fma_f32 v[118:119], v[118:119], v[122:123], v[126:127]
	s_waitcnt vmcnt(62)
	v_and_b32_e32 v123, 0xffff0000, v174
	v_cvt_pk_bf16_f32 v122, v118, v119
	global_store_dword v[136:137], v122, off sc0 sc1
	v_lshlrev_b32_e32 v122, 16, v174
	s_waitcnt lgkmcnt(2)
	v_pk_fma_f32 v[118:119], v[118:119], v[130:131], v[122:123]
	s_waitcnt vmcnt(62)
	v_and_b32_e32 v123, 0xffff0000, v176
	v_cvt_pk_bf16_f32 v122, v118, v119
	global_store_dword v[142:143], v122, off sc0 sc1
	v_lshlrev_b32_e32 v122, 16, v176
	s_waitcnt lgkmcnt(1)
	v_pk_fma_f32 v[118:119], v[118:119], v[134:135], v[122:123]
	s_waitcnt vmcnt(62)
	v_and_b32_e32 v123, 0xffff0000, v178
	v_cvt_pk_bf16_f32 v122, v118, v119
	global_store_dword v[146:147], v122, off sc0 sc1
	v_lshlrev_b32_e32 v122, 16, v178
	s_waitcnt lgkmcnt(0)
	v_pk_fma_f32 v[118:119], v[118:119], v[222:223], v[122:123]
	s_mul_i32 s0, s14, 0x900
	v_cvt_pk_bf16_f32 v122, v118, v119
	global_store_dword v[160:161], v122, off sc0 sc1
	v_add_u32_e32 v122, s0, v6
	ds_read_b64 v[122:123], v122
	s_mul_i32 s0, s14, 0xa00
	v_add_u32_e32 v130, s0, v6
	s_mul_i32 s0, s14, 0xb00
	v_add_u32_e32 v134, s0, v6
	s_mul_i32 s0, s14, 0xc00
	s_waitcnt vmcnt(62)
	v_lshlrev_b32_e32 v126, 16, v180
	v_and_b32_e32 v127, 0xffff0000, v180
	v_add_u32_e32 v136, s0, v6
	ds_read_b64 v[130:131], v130
	ds_read_b64 v[134:135], v134
	ds_read_b64 v[136:137], v136
	s_waitcnt lgkmcnt(3)
	v_pk_fma_f32 v[118:119], v[118:119], v[122:123], v[126:127]
	s_mul_i32 s0, s14, 0xd00
	v_cvt_pk_bf16_f32 v122, v118, v119
	global_store_dword v[110:111], v122, off sc0 sc1
	v_lshlrev_b32_e32 v110, 16, v182
	v_and_b32_e32 v111, 0xffff0000, v182
	s_waitcnt lgkmcnt(2)
	v_pk_fma_f32 v[110:111], v[118:119], v[130:131], v[110:111]
	v_lshl_add_u32 v122, s14, 12, v6
	v_cvt_pk_bf16_f32 v118, v110, v111
	global_store_dword v[106:107], v118, off sc0 sc1
	s_waitcnt vmcnt(62)
	v_lshlrev_b32_e32 v106, 16, v184
	v_and_b32_e32 v107, 0xffff0000, v184
	s_waitcnt lgkmcnt(1)
	v_pk_fma_f32 v[106:107], v[110:111], v[134:135], v[106:107]
	v_mad_i64_i32 v[146:147], s[18:19], s14, v157, v[2:3]
	v_cvt_pk_bf16_f32 v110, v106, v107
	global_store_dword v[102:103], v110, off sc0 sc1
	v_lshlrev_b32_e32 v102, 16, v186
	v_and_b32_e32 v103, 0xffff0000, v186
	s_waitcnt lgkmcnt(0)
	v_pk_fma_f32 v[102:103], v[106:107], v[136:137], v[102:103]
	s_waitcnt vmcnt(62)
	v_and_b32_e32 v107, 0xffff0000, v188
	v_cvt_pk_bf16_f32 v106, v102, v103
	global_store_dword v[98:99], v106, off sc0 sc1
	v_add_u32_e32 v98, s0, v6
	ds_read_b64 v[98:99], v98
	s_mul_i32 s0, s14, 0xe00
	v_add_u32_e32 v110, s0, v6
	s_mul_i32 s0, s14, 0xf00
	v_lshlrev_b32_e32 v106, 16, v188
	v_add_u32_e32 v118, s0, v6
	ds_read_b64 v[110:111], v110
	ds_read_b64 v[118:119], v118
	ds_read_b64 v[122:123], v122
	s_waitcnt lgkmcnt(3)
	v_pk_fma_f32 v[98:99], v[102:103], v[98:99], v[106:107]
	s_mul_i32 s0, s14, 0x1100
	v_cvt_pk_bf16_f32 v102, v98, v99
	global_store_dword v[94:95], v102, off sc0 sc1
	s_waitcnt vmcnt(62)
	v_lshlrev_b32_e32 v94, 16, v190
	v_and_b32_e32 v95, 0xffff0000, v190
	s_waitcnt lgkmcnt(2)
	v_pk_fma_f32 v[94:95], v[98:99], v[110:111], v[94:95]
	v_lshl_add_u64 v[142:143], v[146:147], 0, s[20:21]
	v_cvt_pk_bf16_f32 v98, v94, v95
	global_store_dword v[90:91], v98, off sc0 sc1
	v_lshlrev_b32_e32 v90, 16, v192
	v_and_b32_e32 v91, 0xffff0000, v192
	s_waitcnt lgkmcnt(1)
	v_pk_fma_f32 v[90:91], v[94:95], v[118:119], v[90:91]
	v_lshl_add_u64 v[136:137], v[142:143], 0, s[20:21]
	v_cvt_pk_bf16_f32 v94, v90, v91
	global_store_dword v[86:87], v94, off sc0 sc1
	s_waitcnt vmcnt(62)
	v_lshlrev_b32_e32 v86, 16, v194
	v_and_b32_e32 v87, 0xffff0000, v194
	s_waitcnt lgkmcnt(0)
	v_pk_fma_f32 v[86:87], v[90:91], v[122:123], v[86:87]
	v_and_b32_e32 v91, 0xffff0000, v196
	v_cvt_pk_bf16_f32 v90, v86, v87
	global_store_dword v[82:83], v90, off sc0 sc1
	v_add_u32_e32 v82, s0, v6
	ds_read_b64 v[82:83], v82
	s_mul_i32 s0, s14, 0x1200
	v_add_u32_e32 v94, s0, v6
	s_mul_i32 s0, s14, 0x1300
	v_add_u32_e32 v98, s0, v6
	s_mul_i32 s0, s14, 0x1400
	v_lshlrev_b32_e32 v90, 16, v196
	v_add_u32_e32 v102, s0, v6
	ds_read_b64 v[94:95], v94
	ds_read_b64 v[98:99], v98
	ds_read_b64 v[102:103], v102
	s_waitcnt lgkmcnt(3)
	v_pk_fma_f32 v[82:83], v[86:87], v[82:83], v[90:91]
	s_mul_i32 s0, s14, 0x1500
	v_cvt_pk_bf16_f32 v86, v82, v83
	global_store_dword v[78:79], v86, off sc0 sc1
	s_waitcnt vmcnt(62)
	v_lshlrev_b32_e32 v78, 16, v198
	v_and_b32_e32 v79, 0xffff0000, v198
	s_waitcnt lgkmcnt(2)
	v_pk_fma_f32 v[78:79], v[82:83], v[94:95], v[78:79]
	v_lshl_add_u64 v[134:135], v[136:137], 0, s[20:21]
	v_cvt_pk_bf16_f32 v82, v78, v79
	global_store_dword v[74:75], v82, off sc0 sc1
	v_lshlrev_b32_e32 v74, 16, v200
	v_and_b32_e32 v75, 0xffff0000, v200
	s_waitcnt lgkmcnt(1)
	v_pk_fma_f32 v[74:75], v[78:79], v[98:99], v[74:75]
	v_lshl_add_u64 v[130:131], v[134:135], 0, s[20:21]
	v_cvt_pk_bf16_f32 v78, v74, v75
	global_store_dword v[70:71], v78, off sc0 sc1
	s_waitcnt vmcnt(62)
	v_lshlrev_b32_e32 v70, 16, v202
	v_and_b32_e32 v71, 0xffff0000, v202
	s_waitcnt lgkmcnt(0)
	v_pk_fma_f32 v[70:71], v[74:75], v[102:103], v[70:71]
	v_and_b32_e32 v75, 0xffff0000, v204
	v_cvt_pk_bf16_f32 v74, v70, v71
	global_store_dword v[66:67], v74, off sc0 sc1
	v_add_u32_e32 v66, s0, v6
	ds_read_b64 v[66:67], v66
	s_mul_i32 s0, s14, 0x1600
	v_add_u32_e32 v78, s0, v6
	s_mul_i32 s0, s14, 0x1700
	v_add_u32_e32 v82, s0, v6
	s_mul_i32 s0, s14, 0x1800
	v_lshlrev_b32_e32 v74, 16, v204
	v_add_u32_e32 v86, s0, v6
	ds_read_b64 v[78:79], v78
	ds_read_b64 v[82:83], v82
	ds_read_b64 v[86:87], v86
	s_waitcnt lgkmcnt(3)
	v_pk_fma_f32 v[66:67], v[70:71], v[66:67], v[74:75]
	s_mul_i32 s0, s14, 0x1900
	v_cvt_pk_bf16_f32 v70, v66, v67
	global_store_dword v[62:63], v70, off sc0 sc1
	s_waitcnt vmcnt(62)
	v_lshlrev_b32_e32 v62, 16, v206
	v_and_b32_e32 v63, 0xffff0000, v206
	s_waitcnt lgkmcnt(2)
	v_pk_fma_f32 v[62:63], v[66:67], v[78:79], v[62:63]
	v_lshl_add_u64 v[126:127], v[130:131], 0, s[20:21]
	v_cvt_pk_bf16_f32 v66, v62, v63
	global_store_dword v[58:59], v66, off sc0 sc1
	v_lshlrev_b32_e32 v58, 16, v208
	v_and_b32_e32 v59, 0xffff0000, v208
	s_waitcnt lgkmcnt(1)
	v_pk_fma_f32 v[58:59], v[62:63], v[82:83], v[58:59]
	v_lshl_add_u64 v[122:123], v[126:127], 0, s[20:21]
	v_cvt_pk_bf16_f32 v62, v58, v59
	global_store_dword v[54:55], v62, off sc0 sc1
	s_waitcnt vmcnt(62)
	v_lshlrev_b32_e32 v54, 16, v210
	v_and_b32_e32 v55, 0xffff0000, v210
	s_waitcnt lgkmcnt(0)
	v_pk_fma_f32 v[54:55], v[58:59], v[86:87], v[54:55]
	v_and_b32_e32 v59, 0xffff0000, v212
	v_cvt_pk_bf16_f32 v58, v54, v55
	global_store_dword v[50:51], v58, off sc0 sc1
	v_add_u32_e32 v50, s0, v6
	ds_read_b64 v[50:51], v50
	s_mul_i32 s0, s14, 0x1a00
	v_add_u32_e32 v62, s0, v6
	s_mul_i32 s0, s14, 0x1b00
	v_add_u32_e32 v66, s0, v6
	s_mul_i32 s0, s14, 0x1c00
	v_lshlrev_b32_e32 v58, 16, v212
	v_add_u32_e32 v70, s0, v6
	ds_read_b64 v[62:63], v62
	ds_read_b64 v[66:67], v66
	ds_read_b64 v[70:71], v70
	s_waitcnt lgkmcnt(3)
	v_pk_fma_f32 v[50:51], v[54:55], v[50:51], v[58:59]
	s_mul_i32 s0, s14, 0x1d00
	v_cvt_pk_bf16_f32 v54, v50, v51
	global_store_dword v[46:47], v54, off sc0 sc1
	s_waitcnt vmcnt(62)
	v_lshlrev_b32_e32 v46, 16, v214
	v_and_b32_e32 v47, 0xffff0000, v214
	s_waitcnt lgkmcnt(2)
	v_pk_fma_f32 v[46:47], v[50:51], v[62:63], v[46:47]
	v_lshl_add_u32 v54, s14, 13, v6
	v_cvt_pk_bf16_f32 v50, v46, v47
	global_store_dword v[42:43], v50, off sc0 sc1
	v_lshlrev_b32_e32 v42, 16, v216
	v_and_b32_e32 v43, 0xffff0000, v216
	s_waitcnt lgkmcnt(1)
	v_pk_fma_f32 v[42:43], v[46:47], v[66:67], v[42:43]
	v_lshl_add_u64 v[118:119], v[122:123], 0, s[20:21]
	v_cvt_pk_bf16_f32 v46, v42, v43
	global_store_dword v[38:39], v46, off sc0 sc1
	s_waitcnt vmcnt(62)
	v_lshlrev_b32_e32 v38, 16, v219
	v_and_b32_e32 v39, 0xffff0000, v219
	s_waitcnt lgkmcnt(0)
	v_pk_fma_f32 v[38:39], v[42:43], v[70:71], v[38:39]
	v_and_b32_e32 v43, 0xffff0000, v221
	v_cvt_pk_bf16_f32 v42, v38, v39
	global_store_dword v[34:35], v42, off sc0 sc1
	v_add_u32_e32 v34, s0, v6
	ds_read_b64 v[34:35], v34
	s_mul_i32 s0, s14, 0x1e00
	v_add_u32_e32 v46, s0, v6
	s_mul_i32 s0, s14, 0x1f00
	v_lshlrev_b32_e32 v42, 16, v221
	v_add_u32_e32 v50, s0, v6
	ds_read_b64 v[46:47], v46
	ds_read_b64 v[50:51], v50
	ds_read_b64 v[222:223], v54
	s_waitcnt lgkmcnt(3)
	v_pk_fma_f32 v[34:35], v[38:39], v[34:35], v[42:43]
	s_waitcnt vmcnt(60)
	v_lshlrev_b32_e32 v226, 16, v220
	v_cvt_pk_bf16_f32 v38, v34, v35
	global_store_dword v[32:33], v38, off sc0 sc1
	v_lshlrev_b32_e32 v32, 16, v115
	v_and_b32_e32 v33, 0xffff0000, v115
	s_waitcnt lgkmcnt(2)
	v_pk_fma_f32 v[32:33], v[34:35], v[46:47], v[32:33]
	v_and_b32_e32 v227, 0xffff0000, v220
	v_cvt_pk_bf16_f32 v34, v32, v33
	global_store_dword v[30:31], v34, off sc0 sc1
	v_lshlrev_b32_e32 v30, 16, v114
	v_and_b32_e32 v31, 0xffff0000, v114
	v_lshl_add_u64 v[114:115], v[118:119], 0, s[20:21]
	v_lshl_add_u64 v[110:111], v[114:115], 0, s[20:21]
	v_lshl_add_u64 v[106:107], v[110:111], 0, s[20:21]
	v_lshl_add_u64 v[102:103], v[106:107], 0, s[20:21]
	v_lshl_add_u64 v[98:99], v[102:103], 0, s[20:21]
	v_lshl_add_u64 v[94:95], v[98:99], 0, s[20:21]
	v_lshl_add_u64 v[90:91], v[94:95], 0, s[20:21]
	v_lshl_add_u64 v[86:87], v[90:91], 0, s[20:21]
	v_lshl_add_u64 v[82:83], v[86:87], 0, s[20:21]
	v_lshl_add_u64 v[78:79], v[82:83], 0, s[20:21]
	v_lshl_add_u64 v[74:75], v[78:79], 0, s[20:21]
	v_lshl_add_u64 v[70:71], v[74:75], 0, s[20:21]
	v_lshl_add_u64 v[66:67], v[70:71], 0, s[20:21]
	v_lshl_add_u64 v[62:63], v[66:67], 0, s[20:21]
	v_lshl_add_u64 v[58:59], v[62:63], 0, s[20:21]
	v_lshl_add_u64 v[54:55], v[58:59], 0, s[20:21]
	s_waitcnt lgkmcnt(1)
	v_pk_fma_f32 v[224:225], v[32:33], v[50:51], v[30:31]
	v_lshl_add_u64 v[50:51], v[54:55], 0, s[20:21]
	v_lshl_add_u64 v[46:47], v[50:51], 0, s[20:21]
	v_lshl_add_u64 v[42:43], v[46:47], 0, s[20:21]
	v_lshl_add_u64 v[38:39], v[42:43], 0, s[20:21]
	v_cvt_pk_bf16_f32 v30, v224, v225
	v_lshl_add_u64 v[34:35], v[38:39], 0, s[20:21]
	s_waitcnt lgkmcnt(0)
	v_pk_fma_f32 v[222:223], v[224:225], v[222:223], v[226:227]
	global_store_dword v[28:29], v30, off sc0 sc1
	v_lshl_add_u64 v[32:33], v[34:35], 0, s[20:21]
	v_cvt_pk_bf16_f32 v220, v222, v223
	s_mul_i32 s0, s14, 0x2100
	global_load_dword v221, v[146:147], off
	global_load_dword v219, v[142:143], off
	global_load_dword v216, v[136:137], off
	global_load_dword v214, v[134:135], off
	global_load_dword v212, v[130:131], off
	global_load_dword v210, v[126:127], off
	global_load_dword v208, v[122:123], off
	global_load_dword v206, v[118:119], off
	global_load_dword v204, v[114:115], off
	global_load_dword v202, v[110:111], off
	global_load_dword v200, v[106:107], off
	global_load_dword v198, v[102:103], off
	global_load_dword v196, v[98:99], off
	global_load_dword v194, v[94:95], off
	global_load_dword v192, v[90:91], off
	global_load_dword v190, v[86:87], off
	global_load_dword v188, v[82:83], off
	global_load_dword v186, v[78:79], off
	global_load_dword v184, v[74:75], off
	global_load_dword v182, v[70:71], off
	global_load_dword v180, v[66:67], off
	global_load_dword v178, v[62:63], off
	global_load_dword v176, v[58:59], off
	global_load_dword v174, v[54:55], off
	global_load_dword v172, v[50:51], off
	global_load_dword v170, v[46:47], off
	global_load_dword v168, v[42:43], off
	global_load_dword v166, v[38:39], off
	global_load_dword v164, v[34:35], off
	global_load_dword v162, v[32:33], off
	s_waitcnt vmcnt(62)
	v_lshlrev_b32_e32 v224, 16, v218
	global_store_dword v[148:149], v220, off sc0 sc1
	v_add_u32_e32 v148, s0, v6
	ds_read_b64 v[148:149], v148
	s_mul_i32 s0, s14, 0x2200
	v_and_b32_e32 v225, 0xffff0000, v218
	v_add_u32_e32 v218, s0, v6
	s_mul_i32 s0, s14, 0x2300
	v_lshl_add_u64 v[30:31], v[32:33], 0, s[20:21]
	v_add_u32_e32 v220, s0, v6
	s_mul_i32 s0, s14, 0x2400
	v_lshl_add_u64 v[28:29], v[30:31], 0, s[20:21]
	v_add_u32_e32 v230, s0, v6
	global_load_dword v161, v[30:31], off
	global_load_dword v160, v[28:29], off
	ds_read_b64 v[226:227], v218
	ds_read_b64 v[228:229], v220
	ds_read_b64 v[230:231], v230
	s_waitcnt lgkmcnt(3)
	v_pk_fma_f32 v[148:149], v[222:223], v[148:149], v[224:225]
	s_mul_i32 s0, s14, 0x2500
	v_cvt_pk_bf16_f32 v218, v148, v149
	global_store_dword v[144:145], v218, off sc0 sc1
	v_lshlrev_b32_e32 v144, 16, v217
	v_and_b32_e32 v145, 0xffff0000, v217
	s_waitcnt lgkmcnt(2)
	v_pk_fma_f32 v[144:145], v[148:149], v[226:227], v[144:145]
	s_and_b64 s[16:17], s[16:17], exec
	v_cvt_pk_bf16_f32 v148, v144, v145
	global_store_dword v[140:141], v148, off sc0 sc1
	v_lshlrev_b32_e32 v140, 16, v215
	v_and_b32_e32 v141, 0xffff0000, v215
	s_waitcnt lgkmcnt(1)
	v_pk_fma_f32 v[140:141], v[144:145], v[228:229], v[140:141]
	s_waitcnt vmcnt(34)
	v_lshlrev_b32_e32 v220, 16, v221
	v_cvt_pk_bf16_f32 v144, v140, v141
	global_store_dword v[138:139], v144, off sc0 sc1
	v_lshlrev_b32_e32 v138, 16, v213
	v_and_b32_e32 v139, 0xffff0000, v213
	s_waitcnt lgkmcnt(0)
	v_pk_fma_f32 v[138:139], v[140:141], v[230:231], v[138:139]
	v_and_b32_e32 v141, 0xffff0000, v211
	v_cvt_pk_bf16_f32 v140, v138, v139
	global_store_dword v[132:133], v140, off sc0 sc1
	v_add_u32_e32 v132, s0, v6
	ds_read_b64 v[132:133], v132
	s_mul_i32 s0, s14, 0x2600
	v_add_u32_e32 v144, s0, v6
	s_mul_i32 s0, s14, 0x2700
	v_lshlrev_b32_e32 v140, 16, v211
	v_add_u32_e32 v148, s0, v6
	s_mul_i32 s0, s14, 0x2800
	v_add_u32_e32 v211, s0, v6
	ds_read_b64 v[144:145], v144
	ds_read_b64 v[148:149], v148
	ds_read_b64 v[222:223], v211
	s_waitcnt lgkmcnt(3)
	v_pk_fma_f32 v[132:133], v[138:139], v[132:133], v[140:141]
	s_mul_i32 s0, s14, 0x2900
	v_cvt_pk_bf16_f32 v138, v132, v133
	global_store_dword v[128:129], v138, off sc0 sc1
	v_lshlrev_b32_e32 v128, 16, v209
	v_and_b32_e32 v129, 0xffff0000, v209
	s_waitcnt lgkmcnt(2)
	v_pk_fma_f32 v[128:129], v[132:133], v[144:145], v[128:129]
	v_mad_i64_i32 v[140:141], s[16:17], s14, v158, v[2:3]
	v_cvt_pk_bf16_f32 v132, v128, v129
	global_store_dword v[124:125], v132, off sc0 sc1
	v_lshlrev_b32_e32 v124, 16, v207
	v_and_b32_e32 v125, 0xffff0000, v207
	s_waitcnt lgkmcnt(1)
	v_pk_fma_f32 v[124:125], v[128:129], v[148:149], v[124:125]
	v_and_b32_e32 v221, 0xffff0000, v221
	v_cvt_pk_bf16_f32 v128, v124, v125
	global_store_dword v[120:121], v128, off sc0 sc1
	v_lshlrev_b32_e32 v120, 16, v205
	v_and_b32_e32 v121, 0xffff0000, v205
	s_waitcnt lgkmcnt(0)
	v_pk_fma_f32 v[120:121], v[124:125], v[222:223], v[120:121]
	v_and_b32_e32 v125, 0xffff0000, v203
	v_cvt_pk_bf16_f32 v124, v120, v121
	global_store_dword v[116:117], v124, off sc0 sc1
	v_add_u32_e32 v116, s0, v6
	ds_read_b64 v[116:117], v116
	s_mul_i32 s0, s14, 0x2a00
	v_add_u32_e32 v128, s0, v6
	s_mul_i32 s0, s14, 0x2b00
	v_add_u32_e32 v132, s0, v6
	s_mul_i32 s0, s14, 0x2c00
	v_lshlrev_b32_e32 v124, 16, v203
	v_add_u32_e32 v138, s0, v6
	ds_read_b64 v[128:129], v128
	ds_read_b64 v[132:133], v132
	ds_read_b64 v[138:139], v138
	s_waitcnt lgkmcnt(3)
	v_pk_fma_f32 v[116:117], v[120:121], v[116:117], v[124:125]
	s_mul_i32 s0, s14, 0x2d00
	v_cvt_pk_bf16_f32 v120, v116, v117
	global_store_dword v[112:113], v120, off sc0 sc1
	v_lshlrev_b32_e32 v112, 16, v201
	v_and_b32_e32 v113, 0xffff0000, v201
	s_waitcnt lgkmcnt(2)
	v_pk_fma_f32 v[112:113], v[116:117], v[128:129], v[112:113]
	s_waitcnt vmcnt(40)
	v_lshlrev_b32_e32 v218, 16, v219
	v_cvt_pk_bf16_f32 v116, v112, v113
	global_store_dword v[108:109], v116, off sc0 sc1
	v_lshlrev_b32_e32 v108, 16, v199
	v_and_b32_e32 v109, 0xffff0000, v199
	s_waitcnt lgkmcnt(1)
	v_pk_fma_f32 v[108:109], v[112:113], v[132:133], v[108:109]
	v_and_b32_e32 v219, 0xffff0000, v219
	v_cvt_pk_bf16_f32 v112, v108, v109
	global_store_dword v[104:105], v112, off sc0 sc1
	v_lshlrev_b32_e32 v104, 16, v197
	v_and_b32_e32 v105, 0xffff0000, v197
	s_waitcnt lgkmcnt(0)
	v_pk_fma_f32 v[104:105], v[108:109], v[138:139], v[104:105]
	v_and_b32_e32 v109, 0xffff0000, v195
	v_cvt_pk_bf16_f32 v108, v104, v105
	global_store_dword v[100:101], v108, off sc0 sc1
	v_add_u32_e32 v100, s0, v6
	ds_read_b64 v[100:101], v100
	s_mul_i32 s0, s14, 0x2e00
	v_add_u32_e32 v112, s0, v6
	s_mul_i32 s0, s14, 0x2f00
	v_add_u32_e32 v116, s0, v6
	s_mul_i32 s0, s14, 0x3000
	v_lshlrev_b32_e32 v108, 16, v195
	v_add_u32_e32 v120, s0, v6
	ds_read_b64 v[112:113], v112
	ds_read_b64 v[116:117], v116
	ds_read_b64 v[120:121], v120
	s_waitcnt lgkmcnt(3)
	v_pk_fma_f32 v[100:101], v[104:105], v[100:101], v[108:109]
	s_mul_i32 s0, s14, 0x3100
	v_cvt_pk_bf16_f32 v104, v100, v101
	global_store_dword v[96:97], v104, off sc0 sc1
	v_lshlrev_b32_e32 v96, 16, v193
	v_and_b32_e32 v97, 0xffff0000, v193
	s_waitcnt lgkmcnt(2)
	v_pk_fma_f32 v[96:97], v[100:101], v[112:113], v[96:97]
	v_lshl_add_u64 v[138:139], v[140:141], 0, s[20:21]
	v_cvt_pk_bf16_f32 v100, v96, v97
	global_store_dword v[92:93], v100, off sc0 sc1
	v_lshlrev_b32_e32 v92, 16, v191
	v_and_b32_e32 v93, 0xffff0000, v191
	s_waitcnt lgkmcnt(1)
	v_pk_fma_f32 v[92:93], v[96:97], v[116:117], v[92:93]
	v_lshl_add_u64 v[132:133], v[138:139], 0, s[20:21]
	v_cvt_pk_bf16_f32 v96, v92, v93
	global_store_dword v[88:89], v96, off sc0 sc1
	v_lshlrev_b32_e32 v88, 16, v189
	v_and_b32_e32 v89, 0xffff0000, v189
	s_waitcnt lgkmcnt(0)
	v_pk_fma_f32 v[88:89], v[92:93], v[120:121], v[88:89]
	v_and_b32_e32 v93, 0xffff0000, v187
	v_cvt_pk_bf16_f32 v92, v88, v89
	global_store_dword v[84:85], v92, off sc0 sc1
	v_add_u32_e32 v84, s0, v6
	ds_read_b64 v[84:85], v84
	s_mul_i32 s0, s14, 0x3200
	v_add_u32_e32 v96, s0, v6
	s_mul_i32 s0, s14, 0x3300
	v_add_u32_e32 v100, s0, v6
	s_mul_i32 s0, s14, 0x3400
	v_lshlrev_b32_e32 v92, 16, v187
	v_add_u32_e32 v104, s0, v6
	ds_read_b64 v[96:97], v96
	ds_read_b64 v[100:101], v100
	ds_read_b64 v[104:105], v104
	s_waitcnt lgkmcnt(3)
	v_pk_fma_f32 v[84:85], v[88:89], v[84:85], v[92:93]
	s_mul_i32 s0, s14, 0x3500
	v_cvt_pk_bf16_f32 v88, v84, v85
	global_store_dword v[80:81], v88, off sc0 sc1
	v_lshlrev_b32_e32 v80, 16, v185
	v_and_b32_e32 v81, 0xffff0000, v185
	s_waitcnt lgkmcnt(2)
	v_pk_fma_f32 v[80:81], v[84:85], v[96:97], v[80:81]
	v_lshl_add_u64 v[128:129], v[132:133], 0, s[20:21]
	v_cvt_pk_bf16_f32 v84, v80, v81
	global_store_dword v[76:77], v84, off sc0 sc1
	v_lshlrev_b32_e32 v76, 16, v183
	v_and_b32_e32 v77, 0xffff0000, v183
	s_waitcnt lgkmcnt(1)
	v_pk_fma_f32 v[76:77], v[80:81], v[100:101], v[76:77]
	v_lshl_add_u64 v[124:125], v[128:129], 0, s[20:21]
	v_cvt_pk_bf16_f32 v80, v76, v77
	global_store_dword v[72:73], v80, off sc0 sc1
	v_lshlrev_b32_e32 v72, 16, v181
	v_and_b32_e32 v73, 0xffff0000, v181
	s_waitcnt lgkmcnt(0)
	v_pk_fma_f32 v[72:73], v[76:77], v[104:105], v[72:73]
	v_and_b32_e32 v77, 0xffff0000, v179
	v_cvt_pk_bf16_f32 v76, v72, v73
	global_store_dword v[68:69], v76, off sc0 sc1
	v_add_u32_e32 v68, s0, v6
	ds_read_b64 v[68:69], v68
	s_mul_i32 s0, s14, 0x3600
	v_add_u32_e32 v80, s0, v6
	s_mul_i32 s0, s14, 0x3700
	v_add_u32_e32 v84, s0, v6
	s_mul_i32 s0, s14, 0x3800
	v_lshlrev_b32_e32 v76, 16, v179
	v_add_u32_e32 v88, s0, v6
	ds_read_b64 v[80:81], v80
	ds_read_b64 v[84:85], v84
	ds_read_b64 v[88:89], v88
	s_waitcnt lgkmcnt(3)
	v_pk_fma_f32 v[68:69], v[72:73], v[68:69], v[76:77]
	s_mul_i32 s0, s14, 0x3900
	v_cvt_pk_bf16_f32 v72, v68, v69
	global_store_dword v[64:65], v72, off sc0 sc1
	v_lshlrev_b32_e32 v64, 16, v177
	v_and_b32_e32 v65, 0xffff0000, v177
	s_waitcnt lgkmcnt(2)
	v_pk_fma_f32 v[64:65], v[68:69], v[80:81], v[64:65]
	v_lshl_add_u64 v[120:121], v[124:125], 0, s[20:21]
	v_cvt_pk_bf16_f32 v68, v64, v65
	global_store_dword v[60:61], v68, off sc0 sc1
	v_lshlrev_b32_e32 v60, 16, v175
	v_and_b32_e32 v61, 0xffff0000, v175
	s_waitcnt lgkmcnt(1)
	v_pk_fma_f32 v[60:61], v[64:65], v[84:85], v[60:61]
	v_lshl_add_u64 v[116:117], v[120:121], 0, s[20:21]
	v_cvt_pk_bf16_f32 v64, v60, v61
	global_store_dword v[56:57], v64, off sc0 sc1
	v_lshlrev_b32_e32 v56, 16, v173
	v_and_b32_e32 v57, 0xffff0000, v173
	s_waitcnt lgkmcnt(0)
	v_pk_fma_f32 v[56:57], v[60:61], v[88:89], v[56:57]
	v_and_b32_e32 v61, 0xffff0000, v171
	v_cvt_pk_bf16_f32 v60, v56, v57
	global_store_dword v[52:53], v60, off sc0 sc1
	v_add_u32_e32 v52, s0, v6
	ds_read_b64 v[52:53], v52
	s_mul_i32 s0, s14, 0x3a00
	v_add_u32_e32 v64, s0, v6
	s_mul_i32 s0, s14, 0x3b00
	v_add_u32_e32 v68, s0, v6
	s_mul_i32 s0, s14, 0x3c00
	v_lshlrev_b32_e32 v60, 16, v171
	v_add_u32_e32 v72, s0, v6
	ds_read_b64 v[64:65], v64
	ds_read_b64 v[68:69], v68
	ds_read_b64 v[72:73], v72
	s_waitcnt lgkmcnt(3)
	v_pk_fma_f32 v[52:53], v[56:57], v[52:53], v[60:61]
	v_lshl_add_u64 v[112:113], v[116:117], 0, s[20:21]
	v_cvt_pk_bf16_f32 v56, v52, v53
	global_store_dword v[48:49], v56, off sc0 sc1
	v_lshlrev_b32_e32 v48, 16, v169
	v_and_b32_e32 v49, 0xffff0000, v169
	s_waitcnt lgkmcnt(2)
	v_pk_fma_f32 v[48:49], v[52:53], v[64:65], v[48:49]
	v_lshl_add_u64 v[108:109], v[112:113], 0, s[20:21]
	v_cvt_pk_bf16_f32 v52, v48, v49
	global_store_dword v[44:45], v52, off sc0 sc1
	v_lshlrev_b32_e32 v44, 16, v167
	v_and_b32_e32 v45, 0xffff0000, v167
	s_waitcnt lgkmcnt(1)
	v_pk_fma_f32 v[44:45], v[48:49], v[68:69], v[44:45]
	s_mul_i32 s0, s14, 0x3d00
	v_cvt_pk_bf16_f32 v48, v44, v45
	global_store_dword v[40:41], v48, off sc0 sc1
	v_lshlrev_b32_e32 v40, 16, v165
	v_and_b32_e32 v41, 0xffff0000, v165
	s_waitcnt lgkmcnt(0)
	v_pk_fma_f32 v[40:41], v[44:45], v[72:73], v[40:41]
	v_lshl_add_u64 v[104:105], v[108:109], 0, s[20:21]
	v_cvt_pk_bf16_f32 v44, v40, v41
	global_store_dword v[36:37], v44, off sc0 sc1
	v_add_u32_e32 v36, s0, v6
	v_lshl_add_u64 v[100:101], v[104:105], 0, s[20:21]
	ds_read_b64 v[36:37], v36
	v_lshl_add_u64 v[96:97], v[100:101], 0, s[20:21]
	v_lshl_add_u64 v[92:93], v[96:97], 0, s[20:21]
	s_mul_i32 s0, s14, 0x3e00
	v_lshl_add_u64 v[88:89], v[92:93], 0, s[20:21]
	v_add_u32_e32 v48, s0, v6
	s_mul_i32 s0, s14, 0x3f00
	v_lshl_add_u64 v[84:85], v[88:89], 0, s[20:21]
	v_lshlrev_b32_e32 v44, 16, v163
	v_and_b32_e32 v45, 0xffff0000, v163
	v_add_u32_e32 v52, s0, v6
	v_lshl_add_u64 v[80:81], v[84:85], 0, s[20:21]
	v_lshl_add_u32 v56, s14, 14, v6
	ds_read_b64 v[48:49], v48
	ds_read_b64 v[52:53], v52
	ds_read_b64 v[222:223], v56
	s_waitcnt lgkmcnt(3)
	v_pk_fma_f32 v[36:37], v[40:41], v[36:37], v[44:45]
	v_lshl_add_u64 v[76:77], v[80:81], 0, s[20:21]
	v_cvt_pk_bf16_f32 v40, v36, v37
	v_lshl_add_u64 v[72:73], v[76:77], 0, s[20:21]
	global_store_dword v[26:27], v40, off sc0 sc1
	v_lshlrev_b32_e32 v26, 16, v21
	v_and_b32_e32 v27, 0xffff0000, v21
	v_lshl_add_u64 v[68:69], v[72:73], 0, s[20:21]
	s_waitcnt lgkmcnt(2)
	v_pk_fma_f32 v[26:27], v[36:37], v[48:49], v[26:27]
	v_lshl_add_u64 v[64:65], v[68:69], 0, s[20:21]
	v_cvt_pk_bf16_f32 v21, v26, v27
	v_lshl_add_u64 v[60:61], v[64:65], 0, s[20:21]
	global_store_dword v[4:5], v21, off sc0 sc1
	v_lshlrev_b32_e32 v4, 16, v23
	v_and_b32_e32 v5, 0xffff0000, v23
	v_lshl_add_u64 v[56:57], v[60:61], 0, s[20:21]
	s_waitcnt lgkmcnt(1)
	v_pk_fma_f32 v[224:225], v[26:27], v[52:53], v[4:5]
	v_lshl_add_u64 v[52:53], v[56:57], 0, s[20:21]
	v_lshl_add_u64 v[48:49], v[52:53], 0, s[20:21]
	v_lshl_add_u64 v[44:45], v[48:49], 0, s[20:21]
	v_lshl_add_u64 v[40:41], v[44:45], 0, s[20:21]
	v_lshl_add_u64 v[36:37], v[40:41], 0, s[20:21]
	v_cvt_pk_bf16_f32 v4, v224, v225
	v_lshl_add_u64 v[26:27], v[36:37], 0, s[20:21]
	global_store_dword v[24:25], v4, off sc0 sc1
	s_cselect_b32 s0, 0, 0xfe0000
	v_lshl_add_u64 v[24:25], v[26:27], 0, s[20:21]
	s_waitcnt lgkmcnt(0)
	v_pk_fma_f32 v[220:221], v[224:225], v[222:223], v[220:221]
	v_lshl_add_u64 v[226:227], v[2:3], 0, s[0:1]
	v_lshl_add_u64 v[4:5], v[24:25], 0, s[20:21]
	v_cvt_pk_bf16_f32 v211, v220, v221
	s_mul_i32 s0, s14, 0x4100
	global_load_dword v203, v[124:125], off
	global_load_dword v201, v[120:121], off
	global_load_dword v199, v[116:117], off
	global_load_dword v197, v[112:113], off
	global_load_dword v195, v[108:109], off
	global_load_dword v193, v[104:105], off
	global_load_dword v191, v[100:101], off
	global_load_dword v189, v[96:97], off
	global_load_dword v187, v[92:93], off
	global_load_dword v185, v[88:89], off
	global_load_dword v183, v[84:85], off
	global_load_dword v181, v[80:81], off
	global_load_dword v179, v[76:77], off
	global_load_dword v177, v[72:73], off
	global_load_dword v175, v[68:69], off
	global_load_dword v173, v[64:65], off
	global_load_dword v171, v[60:61], off
	global_load_dword v169, v[56:57], off
	global_load_dword v167, v[52:53], off
	global_load_dword v165, v[48:49], off
	global_load_dword v163, v[44:45], off
	global_load_dword v149, v[40:41], off
	global_load_dword v148, v[36:37], off
	global_load_dword v145, v[26:27], off
	global_load_dword v144, v[24:25], off
	global_load_dword v23, v[4:5], off
	global_load_dword v205, v[140:141], off
	global_load_dword v207, v[138:139], off
	global_load_dword v209, v[132:133], off
	global_load_dword v213, v[128:129], off
	global_load_dword v21, v[226:227], off
	s_andn2_b64 vcc, exec, s[10:11]
	global_store_dword v[146:147], v211, off sc0 sc1
	v_add_u32_e32 v146, s0, v6
	ds_read_b64 v[146:147], v146
	s_mul_i32 s0, s14, 0x4200
	v_add_u32_e32 v211, s0, v6
	s_mul_i32 s0, s14, 0x4300
	v_add_u32_e32 v215, s0, v6
	s_mul_i32 s0, s14, 0x4400
	v_add_u32_e32 v217, s0, v6
	ds_read_b64 v[222:223], v211
	ds_read_b64 v[224:225], v215
	ds_read_b64 v[226:227], v217
	s_waitcnt lgkmcnt(3)
	v_pk_fma_f32 v[146:147], v[220:221], v[146:147], v[218:219]
	s_mul_i32 s0, s14, 0x4500
	v_cvt_pk_bf16_f32 v211, v146, v147
	global_store_dword v[142:143], v211, off sc0 sc1
	s_waitcnt vmcnt(62)
	v_lshlrev_b32_e32 v142, 16, v216
	v_and_b32_e32 v143, 0xffff0000, v216
	s_waitcnt lgkmcnt(2)
	v_pk_fma_f32 v[142:143], v[146:147], v[222:223], v[142:143]
	s_nop 0
	v_cvt_pk_bf16_f32 v146, v142, v143
	global_store_dword v[136:137], v146, off sc0 sc1
	v_lshlrev_b32_e32 v136, 16, v214
	v_and_b32_e32 v137, 0xffff0000, v214
	s_waitcnt lgkmcnt(1)
	v_pk_fma_f32 v[136:137], v[142:143], v[224:225], v[136:137]
	s_nop 0
	v_cvt_pk_bf16_f32 v142, v136, v137
	global_store_dword v[134:135], v142, off sc0 sc1
	v_lshlrev_b32_e32 v134, 16, v212
	v_and_b32_e32 v135, 0xffff0000, v212
	s_waitcnt lgkmcnt(0)
	v_pk_fma_f32 v[134:135], v[136:137], v[226:227], v[134:135]
	v_and_b32_e32 v137, 0xffff0000, v210
	v_cvt_pk_bf16_f32 v136, v134, v135
	global_store_dword v[130:131], v136, off sc0 sc1
	v_add_u32_e32 v130, s0, v6
	ds_read_b64 v[130:131], v130
	s_mul_i32 s0, s14, 0x4600
	v_add_u32_e32 v142, s0, v6
	s_mul_i32 s0, s14, 0x4700
	v_add_u32_e32 v146, s0, v6
	s_mul_i32 s0, s14, 0x4800
	v_lshlrev_b32_e32 v136, 16, v210
	v_add_u32_e32 v210, s0, v6
	ds_read_b64 v[142:143], v142
	ds_read_b64 v[146:147], v146
	ds_read_b64 v[210:211], v210
	s_waitcnt lgkmcnt(3)
	v_pk_fma_f32 v[130:131], v[134:135], v[130:131], v[136:137]
	s_mul_i32 s0, s14, 0x4900
	v_cvt_pk_bf16_f32 v134, v130, v131
	global_store_dword v[126:127], v134, off sc0 sc1
	v_lshlrev_b32_e32 v126, 16, v208
	v_and_b32_e32 v127, 0xffff0000, v208
	s_waitcnt lgkmcnt(2)
	v_pk_fma_f32 v[126:127], v[130:131], v[142:143], v[126:127]
	s_nop 0
	v_cvt_pk_bf16_f32 v130, v126, v127
	global_store_dword v[122:123], v130, off sc0 sc1
	v_lshlrev_b32_e32 v122, 16, v206
	v_and_b32_e32 v123, 0xffff0000, v206
	s_waitcnt lgkmcnt(1)
	v_pk_fma_f32 v[122:123], v[126:127], v[146:147], v[122:123]
	s_nop 0
	v_cvt_pk_bf16_f32 v126, v122, v123
	global_store_dword v[118:119], v126, off sc0 sc1
	v_lshlrev_b32_e32 v118, 16, v204
	v_and_b32_e32 v119, 0xffff0000, v204
	s_waitcnt lgkmcnt(0)
	v_pk_fma_f32 v[118:119], v[122:123], v[210:211], v[118:119]
	v_and_b32_e32 v123, 0xffff0000, v202
	v_cvt_pk_bf16_f32 v122, v118, v119
	global_store_dword v[114:115], v122, off sc0 sc1
	v_add_u32_e32 v114, s0, v6
	ds_read_b64 v[114:115], v114
	s_mul_i32 s0, s14, 0x4a00
	v_add_u32_e32 v126, s0, v6
	s_mul_i32 s0, s14, 0x4b00
	v_add_u32_e32 v130, s0, v6
	s_mul_i32 s0, s14, 0x4c00
	v_lshlrev_b32_e32 v122, 16, v202
	v_add_u32_e32 v134, s0, v6
	ds_read_b64 v[126:127], v126
	ds_read_b64 v[130:131], v130
	ds_read_b64 v[134:135], v134
	s_waitcnt lgkmcnt(3)
	v_pk_fma_f32 v[114:115], v[118:119], v[114:115], v[122:123]
	s_mul_i32 s0, s14, 0x4d00
	v_cvt_pk_bf16_f32 v118, v114, v115
	global_store_dword v[110:111], v118, off sc0 sc1
	v_lshlrev_b32_e32 v110, 16, v200
	v_and_b32_e32 v111, 0xffff0000, v200
	s_waitcnt lgkmcnt(2)
	v_pk_fma_f32 v[110:111], v[114:115], v[126:127], v[110:111]
	s_nop 0
	v_cvt_pk_bf16_f32 v114, v110, v111
	global_store_dword v[106:107], v114, off sc0 sc1
	v_lshlrev_b32_e32 v106, 16, v198
	v_and_b32_e32 v107, 0xffff0000, v198
	s_waitcnt lgkmcnt(1)
	v_pk_fma_f32 v[106:107], v[110:111], v[130:131], v[106:107]
	s_nop 0
	v_cvt_pk_bf16_f32 v110, v106, v107
	global_store_dword v[102:103], v110, off sc0 sc1
	v_lshlrev_b32_e32 v102, 16, v196
	v_and_b32_e32 v103, 0xffff0000, v196
	s_waitcnt lgkmcnt(0)
	v_pk_fma_f32 v[102:103], v[106:107], v[134:135], v[102:103]
	v_and_b32_e32 v107, 0xffff0000, v194
	v_cvt_pk_bf16_f32 v106, v102, v103
	global_store_dword v[98:99], v106, off sc0 sc1
	v_add_u32_e32 v98, s0, v6
	ds_read_b64 v[98:99], v98
	s_mul_i32 s0, s14, 0x4e00
	v_add_u32_e32 v110, s0, v6
	s_mul_i32 s0, s14, 0x4f00
	v_add_u32_e32 v114, s0, v6
	s_mul_i32 s0, s14, 0x5000
	v_lshlrev_b32_e32 v106, 16, v194
	v_add_u32_e32 v118, s0, v6
	ds_read_b64 v[110:111], v110
	ds_read_b64 v[114:115], v114
	ds_read_b64 v[118:119], v118
	s_waitcnt lgkmcnt(3)
	v_pk_fma_f32 v[98:99], v[102:103], v[98:99], v[106:107]
	s_mul_i32 s0, s14, 0x5100
	v_cvt_pk_bf16_f32 v102, v98, v99
	global_store_dword v[94:95], v102, off sc0 sc1
	v_lshlrev_b32_e32 v94, 16, v192
	v_and_b32_e32 v95, 0xffff0000, v192
	s_waitcnt lgkmcnt(2)
	v_pk_fma_f32 v[94:95], v[98:99], v[110:111], v[94:95]
	s_nop 0
	v_cvt_pk_bf16_f32 v98, v94, v95
	global_store_dword v[90:91], v98, off sc0 sc1
	v_lshlrev_b32_e32 v90, 16, v190
	v_and_b32_e32 v91, 0xffff0000, v190
	s_waitcnt lgkmcnt(1)
	v_pk_fma_f32 v[90:91], v[94:95], v[114:115], v[90:91]
	s_nop 0
	v_cvt_pk_bf16_f32 v94, v90, v91
	global_store_dword v[86:87], v94, off sc0 sc1
	v_lshlrev_b32_e32 v86, 16, v188
	v_and_b32_e32 v87, 0xffff0000, v188
	s_waitcnt lgkmcnt(0)
	v_pk_fma_f32 v[86:87], v[90:91], v[118:119], v[86:87]
	v_and_b32_e32 v91, 0xffff0000, v186
	v_cvt_pk_bf16_f32 v90, v86, v87
	global_store_dword v[82:83], v90, off sc0 sc1
	v_add_u32_e32 v82, s0, v6
	ds_read_b64 v[82:83], v82
	s_mul_i32 s0, s14, 0x5200
	v_add_u32_e32 v94, s0, v6
	s_mul_i32 s0, s14, 0x5300
	v_add_u32_e32 v98, s0, v6
	s_mul_i32 s0, s14, 0x5400
	v_lshlrev_b32_e32 v90, 16, v186
	v_add_u32_e32 v102, s0, v6
	ds_read_b64 v[94:95], v94
	ds_read_b64 v[98:99], v98
	ds_read_b64 v[102:103], v102
	s_waitcnt lgkmcnt(3)
	v_pk_fma_f32 v[82:83], v[86:87], v[82:83], v[90:91]
	s_mul_i32 s0, s14, 0x5500
	v_cvt_pk_bf16_f32 v86, v82, v83
	global_store_dword v[78:79], v86, off sc0 sc1
	v_lshlrev_b32_e32 v78, 16, v184
	v_and_b32_e32 v79, 0xffff0000, v184
	s_waitcnt lgkmcnt(2)
	v_pk_fma_f32 v[78:79], v[82:83], v[94:95], v[78:79]
	s_nop 0
	v_cvt_pk_bf16_f32 v82, v78, v79
	global_store_dword v[74:75], v82, off sc0 sc1
	v_lshlrev_b32_e32 v74, 16, v182
	v_and_b32_e32 v75, 0xffff0000, v182
	s_waitcnt lgkmcnt(1)
	v_pk_fma_f32 v[74:75], v[78:79], v[98:99], v[74:75]
	s_nop 0
	v_cvt_pk_bf16_f32 v78, v74, v75
	global_store_dword v[70:71], v78, off sc0 sc1
	v_lshlrev_b32_e32 v70, 16, v180
	v_and_b32_e32 v71, 0xffff0000, v180
	s_waitcnt lgkmcnt(0)
	v_pk_fma_f32 v[70:71], v[74:75], v[102:103], v[70:71]
	v_and_b32_e32 v75, 0xffff0000, v178
	v_cvt_pk_bf16_f32 v74, v70, v71
	global_store_dword v[66:67], v74, off sc0 sc1
	v_add_u32_e32 v66, s0, v6
	ds_read_b64 v[66:67], v66
	s_mul_i32 s0, s14, 0x5600
	v_add_u32_e32 v78, s0, v6
	s_mul_i32 s0, s14, 0x5700
	v_add_u32_e32 v82, s0, v6
	s_mul_i32 s0, s14, 0x5800
	v_lshlrev_b32_e32 v74, 16, v178
	v_add_u32_e32 v86, s0, v6
	ds_read_b64 v[78:79], v78
	ds_read_b64 v[82:83], v82
	ds_read_b64 v[86:87], v86
	s_waitcnt lgkmcnt(3)
	v_pk_fma_f32 v[66:67], v[70:71], v[66:67], v[74:75]
	s_mul_i32 s0, s14, 0x5900
	v_cvt_pk_bf16_f32 v70, v66, v67
	global_store_dword v[62:63], v70, off sc0 sc1
	v_lshlrev_b32_e32 v62, 16, v176
	v_and_b32_e32 v63, 0xffff0000, v176
	s_waitcnt lgkmcnt(2)
	v_pk_fma_f32 v[62:63], v[66:67], v[78:79], v[62:63]
	s_nop 0
	v_cvt_pk_bf16_f32 v66, v62, v63
	global_store_dword v[58:59], v66, off sc0 sc1
	v_lshlrev_b32_e32 v58, 16, v174
	v_and_b32_e32 v59, 0xffff0000, v174
	s_waitcnt lgkmcnt(1)
	v_pk_fma_f32 v[58:59], v[62:63], v[82:83], v[58:59]
	s_nop 0
	v_cvt_pk_bf16_f32 v62, v58, v59
	global_store_dword v[54:55], v62, off sc0 sc1
	v_lshlrev_b32_e32 v54, 16, v172
	v_and_b32_e32 v55, 0xffff0000, v172
	s_waitcnt lgkmcnt(0)
	v_pk_fma_f32 v[54:55], v[58:59], v[86:87], v[54:55]
	v_and_b32_e32 v59, 0xffff0000, v170
	v_cvt_pk_bf16_f32 v58, v54, v55
	global_store_dword v[50:51], v58, off sc0 sc1
	v_add_u32_e32 v50, s0, v6
	ds_read_b64 v[50:51], v50
	s_mul_i32 s0, s14, 0x5a00
	v_add_u32_e32 v62, s0, v6
	s_mul_i32 s0, s14, 0x5b00
	v_add_u32_e32 v66, s0, v6
	s_mul_i32 s0, s14, 0x5c00
	v_lshlrev_b32_e32 v58, 16, v170
	v_add_u32_e32 v70, s0, v6
	ds_read_b64 v[62:63], v62
	ds_read_b64 v[66:67], v66
	ds_read_b64 v[70:71], v70
	s_waitcnt lgkmcnt(3)
	v_pk_fma_f32 v[50:51], v[54:55], v[50:51], v[58:59]
	s_mul_i32 s0, s14, 0x5d00
	v_cvt_pk_bf16_f32 v54, v50, v51
	global_store_dword v[46:47], v54, off sc0 sc1
	v_lshlrev_b32_e32 v46, 16, v168
	v_and_b32_e32 v47, 0xffff0000, v168
	s_waitcnt lgkmcnt(2)
	v_pk_fma_f32 v[46:47], v[50:51], v[62:63], v[46:47]
	s_nop 0
	v_cvt_pk_bf16_f32 v50, v46, v47
	global_store_dword v[42:43], v50, off sc0 sc1
	v_lshlrev_b32_e32 v42, 16, v166
	v_and_b32_e32 v43, 0xffff0000, v166
	s_waitcnt lgkmcnt(1)
	v_pk_fma_f32 v[42:43], v[46:47], v[66:67], v[42:43]
	s_nop 0
	v_cvt_pk_bf16_f32 v46, v42, v43
	global_store_dword v[38:39], v46, off sc0 sc1
	v_lshlrev_b32_e32 v38, 16, v164
	v_and_b32_e32 v39, 0xffff0000, v164
	s_waitcnt lgkmcnt(0)
	v_pk_fma_f32 v[38:39], v[42:43], v[70:71], v[38:39]
	v_and_b32_e32 v43, 0xffff0000, v162
	v_cvt_pk_bf16_f32 v42, v38, v39
	global_store_dword v[34:35], v42, off sc0 sc1
	v_add_u32_e32 v34, s0, v6
	ds_read_b64 v[34:35], v34
	s_mul_i32 s0, s14, 0x5e00
	v_add_u32_e32 v46, s0, v6
	s_mul_i32 s0, s14, 0x5f00
	v_add_u32_e32 v50, s0, v6
	s_mul_i32 s0, s14, 0x6000
	v_lshlrev_b32_e32 v42, 16, v162
	v_add_u32_e32 v54, s0, v6
	ds_read_b64 v[46:47], v46
	ds_read_b64 v[50:51], v50
	ds_read_b64 v[54:55], v54
	s_waitcnt lgkmcnt(3)
	v_pk_fma_f32 v[34:35], v[38:39], v[34:35], v[42:43]
	s_mul_i32 s0, s14, 0x6100
	v_cvt_pk_bf16_f32 v38, v34, v35
	global_store_dword v[32:33], v38, off sc0 sc1
	v_lshlrev_b32_e32 v32, 16, v161
	v_and_b32_e32 v33, 0xffff0000, v161
	s_waitcnt lgkmcnt(2)
	v_pk_fma_f32 v[32:33], v[34:35], v[46:47], v[32:33]
	s_nop 0
	v_cvt_pk_bf16_f32 v34, v32, v33
	global_store_dword v[30:31], v34, off sc0 sc1
	v_lshlrev_b32_e32 v30, 16, v160
	v_and_b32_e32 v31, 0xffff0000, v160
	s_waitcnt lgkmcnt(1)
	v_pk_fma_f32 v[30:31], v[32:33], v[50:51], v[30:31]
	s_waitcnt vmcnt(34)
	v_and_b32_e32 v33, 0xffff0000, v207
	v_cvt_pk_bf16_f32 v32, v30, v31
	global_store_dword v[28:29], v32, off sc0 sc1
	v_lshlrev_b32_e32 v28, 16, v205
	v_and_b32_e32 v29, 0xffff0000, v205
	s_waitcnt lgkmcnt(0)
	v_pk_fma_f32 v[28:29], v[30:31], v[54:55], v[28:29]
	v_lshlrev_b32_e32 v32, 16, v207
	v_cvt_pk_bf16_f32 v30, v28, v29
	global_store_dword v[140:141], v30, off sc0 sc1
	v_add_u32_e32 v30, s0, v6
	ds_read_b64 v[30:31], v30
	s_mul_i32 s0, s14, 0x6200
	v_add_u32_e32 v34, s0, v6
	s_mul_i32 s0, s14, 0x6300
	v_add_u32_e32 v38, s0, v6
	s_mul_i32 s0, s14, 0x6400
	v_add_u32_e32 v42, s0, v6
	ds_read_b64 v[34:35], v34
	ds_read_b64 v[38:39], v38
	ds_read_b64 v[42:43], v42
	s_waitcnt lgkmcnt(3)
	v_pk_fma_f32 v[28:29], v[28:29], v[30:31], v[32:33]
	s_waitcnt vmcnt(35)
	v_and_b32_e32 v31, 0xffff0000, v209
	v_cvt_pk_bf16_f32 v30, v28, v29
	global_store_dword v[138:139], v30, off sc0 sc1
	v_lshlrev_b32_e32 v30, 16, v209
	s_waitcnt lgkmcnt(2)
	v_pk_fma_f32 v[28:29], v[28:29], v[34:35], v[30:31]
	s_waitcnt vmcnt(35)
	v_and_b32_e32 v31, 0xffff0000, v213
	v_cvt_pk_bf16_f32 v30, v28, v29
	global_store_dword v[132:133], v30, off sc0 sc1
	v_lshlrev_b32_e32 v30, 16, v213
	s_waitcnt lgkmcnt(1)
	v_pk_fma_f32 v[28:29], v[28:29], v[38:39], v[30:31]
	v_and_b32_e32 v31, 0xffff0000, v203
	v_cvt_pk_bf16_f32 v30, v28, v29
	global_store_dword v[128:129], v30, off sc0 sc1
	v_lshlrev_b32_e32 v30, 16, v203
	s_waitcnt lgkmcnt(0)
	v_pk_fma_f32 v[28:29], v[28:29], v[42:43], v[30:31]
	s_mul_i32 s0, s14, 0x6500
	v_cvt_pk_bf16_f32 v30, v28, v29
	global_store_dword v[124:125], v30, off sc0 sc1
	v_add_u32_e32 v30, s0, v6
	ds_read_b64 v[30:31], v30
	s_mul_i32 s0, s14, 0x6600
	v_add_u32_e32 v34, s0, v6
	s_mul_i32 s0, s14, 0x6700
	v_add_u32_e32 v38, s0, v6
	s_mul_i32 s0, s14, 0x6800
	v_lshlrev_b32_e32 v32, 16, v201
	v_and_b32_e32 v33, 0xffff0000, v201
	v_add_u32_e32 v42, s0, v6
	ds_read_b64 v[34:35], v34
	ds_read_b64 v[38:39], v38
	ds_read_b64 v[42:43], v42
	s_waitcnt lgkmcnt(3)
	v_pk_fma_f32 v[28:29], v[28:29], v[30:31], v[32:33]
	v_and_b32_e32 v31, 0xffff0000, v199
	v_cvt_pk_bf16_f32 v30, v28, v29
	global_store_dword v[120:121], v30, off sc0 sc1
	v_lshlrev_b32_e32 v30, 16, v199
	s_waitcnt lgkmcnt(2)
	v_pk_fma_f32 v[28:29], v[28:29], v[34:35], v[30:31]
	v_and_b32_e32 v31, 0xffff0000, v197
	v_cvt_pk_bf16_f32 v30, v28, v29
	global_store_dword v[116:117], v30, off sc0 sc1
	v_lshlrev_b32_e32 v30, 16, v197
	s_waitcnt lgkmcnt(1)
	v_pk_fma_f32 v[28:29], v[28:29], v[38:39], v[30:31]
	v_and_b32_e32 v31, 0xffff0000, v195
	v_cvt_pk_bf16_f32 v30, v28, v29
	global_store_dword v[112:113], v30, off sc0 sc1
	v_lshlrev_b32_e32 v30, 16, v195
	s_waitcnt lgkmcnt(0)
	v_pk_fma_f32 v[28:29], v[28:29], v[42:43], v[30:31]
	s_mul_i32 s0, s14, 0x6900
	v_cvt_pk_bf16_f32 v30, v28, v29
	global_store_dword v[108:109], v30, off sc0 sc1
	v_add_u32_e32 v30, s0, v6
	ds_read_b64 v[30:31], v30
	s_mul_i32 s0, s14, 0x6a00
	v_add_u32_e32 v34, s0, v6
	s_mul_i32 s0, s14, 0x6b00
	v_add_u32_e32 v38, s0, v6
	s_mul_i32 s0, s14, 0x6c00
	v_lshlrev_b32_e32 v32, 16, v193
	v_and_b32_e32 v33, 0xffff0000, v193
	v_add_u32_e32 v42, s0, v6
	ds_read_b64 v[34:35], v34
	ds_read_b64 v[38:39], v38
	ds_read_b64 v[42:43], v42
	s_waitcnt lgkmcnt(3)
	v_pk_fma_f32 v[28:29], v[28:29], v[30:31], v[32:33]
	v_and_b32_e32 v31, 0xffff0000, v191
	v_cvt_pk_bf16_f32 v30, v28, v29
	global_store_dword v[104:105], v30, off sc0 sc1
	v_lshlrev_b32_e32 v30, 16, v191
	s_waitcnt lgkmcnt(2)
	v_pk_fma_f32 v[28:29], v[28:29], v[34:35], v[30:31]
	v_and_b32_e32 v31, 0xffff0000, v189
	v_cvt_pk_bf16_f32 v30, v28, v29
	global_store_dword v[100:101], v30, off sc0 sc1
	v_lshlrev_b32_e32 v30, 16, v189
	s_waitcnt lgkmcnt(1)
	v_pk_fma_f32 v[28:29], v[28:29], v[38:39], v[30:31]
	v_and_b32_e32 v31, 0xffff0000, v187
	v_cvt_pk_bf16_f32 v30, v28, v29
	global_store_dword v[96:97], v30, off sc0 sc1
	v_lshlrev_b32_e32 v30, 16, v187
	s_waitcnt lgkmcnt(0)
	v_pk_fma_f32 v[28:29], v[28:29], v[42:43], v[30:31]
	s_mul_i32 s0, s14, 0x6d00
	v_cvt_pk_bf16_f32 v30, v28, v29
	global_store_dword v[92:93], v30, off sc0 sc1
	v_add_u32_e32 v30, s0, v6
	ds_read_b64 v[30:31], v30
	s_mul_i32 s0, s14, 0x6e00
	v_add_u32_e32 v34, s0, v6
	s_mul_i32 s0, s14, 0x6f00
	v_add_u32_e32 v38, s0, v6
	s_mul_i32 s0, s14, 0x7000
	v_lshlrev_b32_e32 v32, 16, v185
	v_and_b32_e32 v33, 0xffff0000, v185
	v_add_u32_e32 v42, s0, v6
	ds_read_b64 v[34:35], v34
	ds_read_b64 v[38:39], v38
	ds_read_b64 v[42:43], v42
	s_waitcnt lgkmcnt(3)
	v_pk_fma_f32 v[28:29], v[28:29], v[30:31], v[32:33]
	v_and_b32_e32 v31, 0xffff0000, v183
	v_cvt_pk_bf16_f32 v30, v28, v29
	global_store_dword v[88:89], v30, off sc0 sc1
	v_lshlrev_b32_e32 v30, 16, v183
	s_waitcnt lgkmcnt(2)
	v_pk_fma_f32 v[28:29], v[28:29], v[34:35], v[30:31]
	v_and_b32_e32 v31, 0xffff0000, v181
	v_cvt_pk_bf16_f32 v30, v28, v29
	global_store_dword v[84:85], v30, off sc0 sc1
	v_lshlrev_b32_e32 v30, 16, v181
	s_waitcnt lgkmcnt(1)
	v_pk_fma_f32 v[28:29], v[28:29], v[38:39], v[30:31]
	v_and_b32_e32 v31, 0xffff0000, v179
	v_cvt_pk_bf16_f32 v30, v28, v29
	global_store_dword v[80:81], v30, off sc0 sc1
	v_lshlrev_b32_e32 v30, 16, v179
	s_waitcnt lgkmcnt(0)
	v_pk_fma_f32 v[28:29], v[28:29], v[42:43], v[30:31]
	s_mul_i32 s0, s14, 0x7100
	v_cvt_pk_bf16_f32 v30, v28, v29
	global_store_dword v[76:77], v30, off sc0 sc1
	v_add_u32_e32 v30, s0, v6
	ds_read_b64 v[30:31], v30
	s_mul_i32 s0, s14, 0x7200
	v_add_u32_e32 v34, s0, v6
	s_mul_i32 s0, s14, 0x7300
	v_add_u32_e32 v38, s0, v6
	s_mul_i32 s0, s14, 0x7400
	v_lshlrev_b32_e32 v32, 16, v177
	v_and_b32_e32 v33, 0xffff0000, v177
	v_add_u32_e32 v42, s0, v6
	ds_read_b64 v[34:35], v34
	ds_read_b64 v[38:39], v38
	ds_read_b64 v[42:43], v42
	s_waitcnt lgkmcnt(3)
	v_pk_fma_f32 v[28:29], v[28:29], v[30:31], v[32:33]
	v_and_b32_e32 v31, 0xffff0000, v175
	v_cvt_pk_bf16_f32 v30, v28, v29
	global_store_dword v[72:73], v30, off sc0 sc1
	v_lshlrev_b32_e32 v30, 16, v175
	s_waitcnt lgkmcnt(2)
	v_pk_fma_f32 v[28:29], v[28:29], v[34:35], v[30:31]
	v_and_b32_e32 v31, 0xffff0000, v173
	v_cvt_pk_bf16_f32 v30, v28, v29
	global_store_dword v[68:69], v30, off sc0 sc1
	v_lshlrev_b32_e32 v30, 16, v173
	s_waitcnt lgkmcnt(1)
	v_pk_fma_f32 v[28:29], v[28:29], v[38:39], v[30:31]
	v_and_b32_e32 v31, 0xffff0000, v171
	v_cvt_pk_bf16_f32 v30, v28, v29
	global_store_dword v[64:65], v30, off sc0 sc1
	v_lshlrev_b32_e32 v30, 16, v171
	s_waitcnt lgkmcnt(0)
	v_pk_fma_f32 v[28:29], v[28:29], v[42:43], v[30:31]
	s_mul_i32 s0, s14, 0x7500
	v_cvt_pk_bf16_f32 v30, v28, v29
	global_store_dword v[60:61], v30, off sc0 sc1
	v_add_u32_e32 v30, s0, v6
	ds_read_b64 v[30:31], v30
	s_mul_i32 s0, s14, 0x7600
	v_add_u32_e32 v34, s0, v6
	s_mul_i32 s0, s14, 0x7700
	v_add_u32_e32 v38, s0, v6
	s_mul_i32 s0, s14, 0x7800
	v_lshlrev_b32_e32 v32, 16, v169
	v_and_b32_e32 v33, 0xffff0000, v169
	v_add_u32_e32 v42, s0, v6
	ds_read_b64 v[34:35], v34
	ds_read_b64 v[38:39], v38
	ds_read_b64 v[42:43], v42
	s_waitcnt lgkmcnt(3)
	v_pk_fma_f32 v[28:29], v[28:29], v[30:31], v[32:33]
	v_and_b32_e32 v31, 0xffff0000, v167
	v_cvt_pk_bf16_f32 v30, v28, v29
	global_store_dword v[56:57], v30, off sc0 sc1
	v_lshlrev_b32_e32 v30, 16, v167
	s_waitcnt lgkmcnt(2)
	v_pk_fma_f32 v[28:29], v[28:29], v[34:35], v[30:31]
	v_and_b32_e32 v31, 0xffff0000, v165
	v_cvt_pk_bf16_f32 v30, v28, v29
	global_store_dword v[52:53], v30, off sc0 sc1
	v_lshlrev_b32_e32 v30, 16, v165
	s_waitcnt lgkmcnt(1)
	v_pk_fma_f32 v[28:29], v[28:29], v[38:39], v[30:31]
	v_and_b32_e32 v31, 0xffff0000, v163
	v_cvt_pk_bf16_f32 v30, v28, v29
	global_store_dword v[48:49], v30, off sc0 sc1
	v_lshlrev_b32_e32 v30, 16, v163
	s_mul_i32 s0, s14, 0x7900
	s_waitcnt lgkmcnt(0)
	v_pk_fma_f32 v[28:29], v[28:29], v[42:43], v[30:31]
	v_add_u32_e32 v38, s0, v6
	s_mul_i32 s0, s14, 0x7a00
	v_cvt_pk_bf16_f32 v30, v28, v29
	v_add_u32_e32 v42, s0, v6
	s_mul_i32 s0, s14, 0x7b00
	global_store_dword v[44:45], v30, off sc0 sc1
	v_add_u32_e32 v44, s0, v6
	s_mul_i32 s0, s14, 0x7c00
	v_add_u32_e32 v46, s0, v6
	ds_read_b64 v[38:39], v38
	ds_read_b64 v[42:43], v42
	ds_read_b64 v[44:45], v44
	ds_read_b64 v[46:47], v46
	v_lshlrev_b32_e32 v30, 16, v149
	v_and_b32_e32 v31, 0xffff0000, v149
	s_mul_i32 s0, s14, 0x7d00
	v_lshlrev_b32_e32 v32, 16, v148
	v_and_b32_e32 v33, 0xffff0000, v148
	v_add_u32_e32 v50, s0, v6
	s_waitcnt lgkmcnt(3)
	v_pk_fma_f32 v[28:29], v[28:29], v[38:39], v[30:31]
	v_lshlrev_b32_e32 v34, 16, v145
	v_and_b32_e32 v35, 0xffff0000, v145
	ds_read_b64 v[50:51], v50
	v_lshlrev_b32_e32 v52, 16, v23
	v_and_b32_e32 v53, 0xffff0000, v23
	v_cvt_pk_bf16_f32 v23, v28, v29
	s_waitcnt lgkmcnt(3)
	v_pk_fma_f32 v[28:29], v[28:29], v[42:43], v[32:33]
	global_store_dword v[40:41], v23, off sc0 sc1
	v_cvt_pk_bf16_f32 v23, v28, v29
	s_waitcnt lgkmcnt(2)
	v_pk_fma_f32 v[28:29], v[28:29], v[44:45], v[34:35]
	v_lshlrev_b32_e32 v48, 16, v144
	v_and_b32_e32 v49, 0xffff0000, v144
	global_store_dword v[36:37], v23, off sc0 sc1
	v_cvt_pk_bf16_f32 v23, v28, v29
	global_store_dword v[26:27], v23, off sc0 sc1
	s_waitcnt lgkmcnt(1)
	v_pk_fma_f32 v[26:27], v[28:29], v[46:47], v[48:49]
	s_nop 0
	v_cvt_pk_bf16_f32 v23, v26, v27
	global_store_dword v[24:25], v23, off sc0 sc1
	s_waitcnt lgkmcnt(0)
	v_pk_fma_f32 v[24:25], v[26:27], v[50:51], v[52:53]
	s_nop 0
	v_cvt_pk_bf16_f32 v23, v24, v25
	global_store_dword v[4:5], v23, off sc0 sc1
	s_cbranch_vccnz .LBB0_1114
	ds_read_b64 v[4:5], v6 offset:32256
	s_waitcnt vmcnt(62)
	v_lshlrev_b32_e32 v26, 16, v21
	v_and_b32_e32 v27, 0xffff0000, v21
	v_mad_u64_u32 v[2:3], s[10:11], s14, v159, v[2:3]
	s_waitcnt lgkmcnt(0)
	v_pk_fma_f32 v[4:5], v[24:25], v[4:5], v[26:27]
	s_mul_i32 s0, s15, 0xfe0000
	v_cvt_pk_bf16_f32 v4, v4, v5
	v_add_u32_e32 v3, s0, v3
	global_store_dword v[2:3], v4, off sc0 sc1
